# filter stage 2 (rides in the hyena-GEMM phase): the 16 hidden-row loads of each lag are issued together instead of four load-wait rounds
# baseline (speedup 1.0000x reference)
; DI void filt2_task(const Params& P, int layer, int set, int o, int cg16, char* smem) {
;     ...
;   for (int tau = sl * nper; tau < (sl + 1) * nper; ++tau) {
;     const float4* hr = (const float4*)(h2 + (size_t)tau * 64);
;     float v0 = b30, v1 = b31;
; #pragma unroll
;     for (int kc = 0; kc < 16; ++kc) {
;       const float4 hv = hr[kc];
;       v0 += hv.x * w3s[(kc * 4 + 0) * 32 + cc] + hv.y * w3s[(kc * 4 + 1) * 32 + cc] + hv.z * w3s[(kc * 4 + 2) * 32 + cc] + hv.w * w3s[(kc * 4 + 3) * 32 + cc];
;       v1 += hv.x * w3s[(kc * 4 + 0) * 32 + 16 + cc] + hv.y * w3s[(kc * 4 + 1) * 32 + 16 + cc] + hv.z * w3s[(kc * 4 + 2) * 32 + 16 + cc] + hv.w * w3s[(kc * 4 + 3) * 32 + 16 + cc];
;     }
;     const float tt = (float)tau / (float)(L - 1);
;     const float dec = expf(-tt * delta);
;     v0 *= dec; v1 *= dec;
;     kr[OFF - tau] = (h16)v0;
;     sum += fabsf(v0);
;     if (tau >= 1) { kr[OFF + tau] = (h16)v1; sum += fabsf(v1); }
.LBB0_480:
	v_readlane_b32 s52, v253, 1
	v_readlane_b32 s66, v253, 15
	v_readlane_b32 s67, v253, 16
	s_mov_b64 s[2:3], 0x2854000
	v_readlane_b32 s53, v253, 2
	v_lshl_add_u64 v[38:39], s[66:67], 0, v[192:193]
	v_add_co_u32_e32 v40, vcc, 0x2854000, v38
	v_lshl_add_u64 v[14:15], v[38:39], 0, s[2:3]
	s_nop 0
	v_addc_co_u32_e32 v41, vcc, 0, v39, vcc
	global_load_dwordx4 v[6:9], v[40:41], off
	global_load_dwordx4 v[2:5], v[14:15], off offset:48
	global_load_dwordx4 v[10:13], v[14:15], off offset:32
	s_nop 0
	global_load_dwordx4 v[14:17], v[14:15], off offset:16
	s_mov_b64 s[2:3], 0x2854040
	v_lshl_add_u64 v[26:27], v[38:39], 0, s[2:3]
	s_mov_b64 s[2:3], 0x2854080
	global_load_dwordx4 v[22:25], v[40:41], off offset:64
	global_load_dwordx4 v[18:21], v[26:27], off offset:48
	global_load_dwordx4 v[30:33], v[26:27], off offset:32
	global_load_dwordx4 v[26:29], v[26:27], off offset:16
	v_lshl_add_u64 v[244:245], v[38:39], 0, s[2:3]
	global_load_dwordx4 v[42:45], v[40:41], off offset:128
	global_load_dwordx4 v[240:243], v[244:245], off offset:48
	global_load_dwordx4 v[46:49], v[244:245], off offset:32
	global_load_dwordx4 v[244:247], v[244:245], off offset:16
	s_mov_b64 s[2:3], 0x28540c0
	v_lshl_add_u64 v[236:237], v[38:39], 0, s[2:3]
	global_load_dwordx4 v[248:251], v[40:41], off offset:192
	global_load_dwordx4 v[228:231], v[236:237], off offset:48
	global_load_dwordx4 v[232:235], v[236:237], off offset:32
	global_load_dwordx4 v[236:239], v[236:237], off offset:16
	v_readlane_b32 s54, v253, 3
	v_readlane_b32 s55, v253, 4
	v_readlane_b32 s56, v253, 5
	v_readlane_b32 s57, v253, 6
	v_readlane_b32 s58, v253, 7
	v_readlane_b32 s59, v253, 8
	v_readlane_b32 s60, v253, 9
	v_readlane_b32 s61, v253, 10
	v_readlane_b32 s62, v253, 11
	v_readlane_b32 s63, v253, 12
	v_readlane_b32 s64, v253, 13
	v_readlane_b32 s65, v253, 14
	s_waitcnt vmcnt(0)
	v_mul_f32_e32 v252, v62, v7
	v_fmac_f32_e32 v252, v60, v6
	v_fmac_f32_e32 v252, v64, v8
	s_waitcnt vmcnt(0)
	v_mul_f32_e32 v227, v70, v15
	v_fmac_f32_e32 v227, v68, v14
	v_fmac_f32_e32 v252, v66, v9
	v_fmac_f32_e32 v227, v72, v16
	v_add_f32_e32 v252, v223, v252
	v_fmac_f32_e32 v227, v74, v17
	v_add_f32_e32 v252, v252, v227
	v_mul_f32_e32 v227, v78, v11
	v_fmac_f32_e32 v227, v76, v10
	v_fmac_f32_e32 v227, v80, v12
	v_fmac_f32_e32 v227, v82, v13
	v_add_f32_e32 v252, v252, v227
	v_mul_f32_e32 v227, v86, v3
	v_fmac_f32_e32 v227, v84, v2
	v_fmac_f32_e32 v227, v88, v4
	v_fmac_f32_e32 v227, v90, v5
	v_add_f32_e32 v34, v252, v227
	s_waitcnt vmcnt(3)
	v_mul_f32_e32 v35, v94, v23
	v_fmac_f32_e32 v35, v92, v22
	v_fmac_f32_e32 v35, v96, v24
	v_fmac_f32_e32 v35, v98, v25
	v_add_f32_e32 v34, v34, v35
	s_waitcnt vmcnt(0)
	v_mul_f32_e32 v35, v102, v27
	v_mov_b32_e32 v195, v18
	v_mov_b32_e32 v18, v31
	v_fmac_f32_e32 v35, v100, v26
	v_mov_b32_e32 v194, v30
	v_pk_mul_f32 v[30:31], v[110:111], v[18:19]
	v_fmac_f32_e32 v35, v104, v28
	v_pk_fma_f32 v[30:31], v[108:109], v[194:195], v[30:31]
	v_mov_b32_e32 v196, v32
	v_mov_b32_e32 v197, v20
	v_fmac_f32_e32 v35, v106, v29
	v_pk_fma_f32 v[30:31], v[112:113], v[196:197], v[30:31]
	v_mov_b32_e32 v20, v33
	v_add_f32_e32 v34, v34, v35
	v_pk_fma_f32 v[30:31], v[114:115], v[20:21], v[30:31]
	s_nop 0
	v_add_f32_e32 v30, v34, v30
	v_add_f32_e32 v50, v30, v31
	v_mov_b32_e32 v30, v240
	v_mov_b32_e32 v31, v241
	v_mov_b32_e32 v32, v242
	v_mov_b32_e32 v33, v243
	v_mov_b32_e32 v34, v244
	v_mov_b32_e32 v35, v245
	v_mov_b32_e32 v36, v246
	v_mov_b32_e32 v37, v247
	s_waitcnt vmcnt(3)
	v_mov_b32_e32 v198, v42
	v_mov_b32_e32 v200, v44
	s_waitcnt vmcnt(2)
	v_mov_b32_e32 v203, v30
	s_waitcnt vmcnt(0)
	v_mov_b32_e32 v199, v34
	v_mov_b32_e32 v34, v43
	v_pk_mul_f32 v[42:43], v[118:119], v[34:35]
	v_mov_b32_e32 v201, v36
	v_pk_fma_f32 v[42:43], v[116:117], v[198:199], v[42:43]
	v_mov_b32_e32 v36, v45
	v_pk_fma_f32 v[42:43], v[120:121], v[200:201], v[42:43]
	v_mov_b32_e32 v30, v47
	v_pk_fma_f32 v[42:43], v[122:123], v[36:37], v[42:43]
	v_mov_b32_e32 v202, v46
	v_add_f32_e32 v42, v50, v42
	v_add_f32_e32 v44, v42, v43
	v_pk_mul_f32 v[42:43], v[126:127], v[30:31]
	v_mov_b32_e32 v204, v48
	v_pk_fma_f32 v[42:43], v[124:125], v[202:203], v[42:43]
	v_mov_b32_e32 v205, v32
	v_pk_fma_f32 v[42:43], v[130:131], v[204:205], v[42:43]
	v_mov_b32_e32 v32, v49
	v_pk_fma_f32 v[42:43], v[132:133], v[32:33], v[42:43]
	s_nop 0
	v_add_f32_e32 v42, v44, v42
	v_add_f32_e32 v59, v42, v43
	v_mov_b32_e32 v50, v248
	v_mov_b32_e32 v51, v249
	v_mov_b32_e32 v52, v250
	v_mov_b32_e32 v53, v251
	v_mov_b32_e32 v38, v228
	v_mov_b32_e32 v39, v229
	v_mov_b32_e32 v40, v230
	v_mov_b32_e32 v41, v231
	v_mov_b32_e32 v46, v232
	v_mov_b32_e32 v47, v233
	v_mov_b32_e32 v48, v234
	v_mov_b32_e32 v49, v235
	v_mov_b32_e32 v42, v236
	v_mov_b32_e32 v43, v237
	v_mov_b32_e32 v44, v238
	v_mov_b32_e32 v45, v239
	s_waitcnt vmcnt(3)
	v_mov_b32_e32 v206, v50
	s_waitcnt vmcnt(0)
	v_mov_b32_e32 v207, v42
	v_mov_b32_e32 v42, v51
	v_pk_mul_f32 v[50:51], v[136:137], v[42:43]
	s_nop 0
	v_pk_fma_f32 v[210:211], v[134:135], v[206:207], v[50:51]
	v_mov_b32_e32 v50, v52
	v_mov_b32_e32 v51, v44
	v_pk_fma_f32 v[210:211], v[138:139], v[50:51], v[210:211]
	v_mov_b32_e32 v44, v53
	v_pk_fma_f32 v[52:53], v[140:141], v[44:45], v[210:211]
	s_nop 0
	v_add_f32_e32 v52, v59, v52
	v_add_f32_e32 v59, v52, v53
	v_mov_b32_e32 v53, v38
	v_mov_b32_e32 v38, v47
	v_mov_b32_e32 v52, v46
	v_pk_mul_f32 v[46:47], v[144:145], v[38:39]
	s_nop 0
	v_pk_fma_f32 v[210:211], v[142:143], v[52:53], v[46:47]
	v_mov_b32_e32 v46, v48
	v_mov_b32_e32 v47, v40
	v_pk_fma_f32 v[210:211], v[146:147], v[46:47], v[210:211]
	v_mov_b32_e32 v40, v49
	v_pk_fma_f32 v[48:49], v[148:149], v[40:41], v[210:211]
	s_nop 0
	v_add_f32_e32 v48, v59, v48
	v_add_f32_e32 v49, v48, v49
	v_cvt_f32_i32_e32 v48, v58
	v_div_scale_f32 v59, s[2:3], v226, v226, -v48
	v_rcp_f32_e32 v128, v59
	s_mov_b32 s2, 0x3fb8aa3b
	v_fma_f32 v210, -v59, v128, 1.0
	v_fmac_f32_e32 v128, v210, v128
	v_div_scale_f32 v210, vcc, -v48, v226, -v48
	v_mul_f32_e32 v211, v210, v128
	v_fma_f32 v212, -v59, v211, v210
	v_fmac_f32_e32 v211, v212, v128
	v_fma_f32 v59, -v59, v211, v210
	v_div_fmas_f32 v59, v59, v128, v211
	v_div_fixup_f32 v48, v59, v226, -v48
	v_mul_f32_e64 v48, |v225|, v48
	v_mul_f32_e32 v59, 0x3fb8aa3b, v48
	v_fma_f32 v128, v48, s2, -v59
	v_rndne_f32_e32 v210, v59
	v_fmac_f32_e32 v128, 0x32a5705f, v48
	v_sub_f32_e32 v59, v59, v210
	v_add_f32_e32 v59, v59, v128
	v_exp_f32_e32 v59, v59
	v_cvt_i32_f32_e32 v128, v210
	s_mov_b32 s2, 0xc2ce8ed0
	v_cmp_ngt_f32_e32 vcc, s2, v48
	s_mov_b32 s2, 0x42b17218
	v_ldexp_f32 v59, v59, v128
	v_cndmask_b32_e32 v59, 0, v59, vcc
	v_cmp_nlt_f32_e32 vcc, s2, v48
	v_lshl_add_u64 v[210:211], s[66:67], 0, v[190:191]
	s_nop 0
	v_cndmask_b32_e32 v48, v219, v59, vcc
	v_mul_f32_e32 v59, v48, v49
	v_fma_mixlo_f16 v49, v48, v49, 0
	v_add_f32_e64 v55, v55, |v59|
	v_cmp_lt_i32_e32 vcc, 0, v58
	global_store_short v[210:211], v49, off
	s_and_saveexec_b64 s[2:3], vcc
	s_cbranch_execz .LBB0_479
; DI void filt2_task(const Params& P, int layer, int set, int o, int cg16, char* smem) {
;     ...
;       v0 += hv.x * w3s[(kc * 4 + 0) * 32 + cc] + hv.y * w3s[(kc * 4 + 1) * 32 + cc] + hv.z * w3s[(kc * 4 + 2) * 32 + cc] + hv.w * w3s[(kc * 4 + 3) * 32 + cc];
;       v1 += hv.x * w3s[(kc * 4 + 0) * 32 + 16 + cc] + hv.y * w3s[(kc * 4 + 1) * 32 + 16 + cc] + hv.z * w3s[(kc * 4 + 2) * 32 + 16 + cc] + hv.w * w3s[(kc * 4 + 3) * 32 + 16 + cc];
;     }
;     const float tt = (float)tau / (float)(L - 1);
;     const float dec = expf(-tt * delta);
;     v0 *= dec; v1 *= dec;
;     kr[OFF - tau] = (h16)v0;
;     sum += fabsf(v0);
;     if (tau >= 1) { kr[OFF + tau] = (h16)v1; sum += fabsf(v1); }
	v_mul_f32_e32 v7, v63, v7
	v_fmac_f32_e32 v7, v61, v6
	v_fmac_f32_e32 v7, v65, v8
	v_fmac_f32_e32 v7, v67, v9
	v_add_f32_e32 v6, v224, v7
	v_mul_f32_e32 v7, v71, v15
	v_fmac_f32_e32 v7, v69, v14
	v_fmac_f32_e32 v7, v73, v16
	v_fmac_f32_e32 v7, v75, v17
	v_add_f32_e32 v6, v6, v7
	v_mul_f32_e32 v7, v79, v11
	v_fmac_f32_e32 v7, v77, v10
	v_mul_f32_e32 v3, v87, v3
	v_fmac_f32_e32 v7, v81, v12
	v_fmac_f32_e32 v3, v85, v2
	v_fmac_f32_e32 v7, v83, v13
	v_fmac_f32_e32 v3, v89, v4
	v_add_f32_e32 v6, v6, v7
	v_fmac_f32_e32 v3, v91, v5
	v_add_f32_e32 v2, v6, v3
	v_mul_f32_e32 v3, v95, v23
	v_fmac_f32_e32 v3, v93, v22
	v_fmac_f32_e32 v3, v97, v24
	v_fmac_f32_e32 v3, v99, v25
	v_add_f32_e32 v2, v2, v3
	v_mul_f32_e32 v3, v103, v27
	v_fmac_f32_e32 v3, v101, v26
	v_fmac_f32_e32 v3, v105, v28
	v_fmac_f32_e32 v3, v107, v29
	v_add_f32_e32 v4, v2, v3
	v_pk_mul_f32 v[2:3], v[184:185], v[18:19]
	v_add_u32_e32 v128, s80, v58
	v_pk_fma_f32 v[2:3], v[182:183], v[194:195], v[2:3]
	s_nop 0
	v_pk_fma_f32 v[2:3], v[186:187], v[196:197], v[2:3]
	s_nop 0
	v_pk_fma_f32 v[2:3], v[188:189], v[20:21], v[2:3]
	s_nop 0
	v_add_f32_e32 v2, v4, v2
	v_add_f32_e32 v4, v2, v3
	v_pk_mul_f32 v[2:3], v[176:177], v[34:35]
	s_nop 0
	v_pk_fma_f32 v[2:3], v[174:175], v[198:199], v[2:3]
	s_nop 0
	v_pk_fma_f32 v[2:3], v[178:179], v[200:201], v[2:3]
	s_nop 0
	v_pk_fma_f32 v[2:3], v[180:181], v[36:37], v[2:3]
	s_nop 0
	v_add_f32_e32 v2, v4, v2
	v_add_f32_e32 v4, v2, v3
	v_pk_mul_f32 v[2:3], v[168:169], v[30:31]
	s_nop 0
	v_pk_fma_f32 v[2:3], v[166:167], v[202:203], v[2:3]
	s_nop 0
	v_pk_fma_f32 v[2:3], v[170:171], v[204:205], v[2:3]
	s_nop 0
	v_pk_fma_f32 v[2:3], v[172:173], v[32:33], v[2:3]
	s_nop 0
	v_add_f32_e32 v2, v4, v2
	v_add_f32_e32 v4, v2, v3
	v_pk_mul_f32 v[2:3], v[160:161], v[42:43]
	s_nop 0
	v_pk_fma_f32 v[2:3], v[158:159], v[206:207], v[2:3]
	s_nop 0
	v_pk_fma_f32 v[2:3], v[162:163], v[50:51], v[2:3]
	s_nop 0
	v_pk_fma_f32 v[2:3], v[164:165], v[44:45], v[2:3]
	s_nop 0
	v_add_f32_e32 v2, v4, v2
	v_add_f32_e32 v4, v2, v3
	v_pk_mul_f32 v[2:3], v[152:153], v[38:39]
	s_nop 0
	v_pk_fma_f32 v[2:3], v[150:151], v[52:53], v[2:3]
	s_nop 0
	v_pk_fma_f32 v[2:3], v[154:155], v[46:47], v[2:3]
	s_nop 0
	v_pk_fma_f32 v[2:3], v[156:157], v[40:41], v[2:3]
	s_nop 0
	v_add_f32_e32 v2, v4, v2
	v_add_f32_e32 v4, v2, v3
	v_mul_f32_e32 v2, v48, v4
	v_add_f32_e64 v55, |v2|, v55
	v_lshl_add_u64 v[2:3], v[128:129], 1, v[56:57]
	v_fma_mixlo_f16 v4, v48, v4, 0
	global_store_short v[2:3], v4, off
	s_branch .LBB0_479
